# dt fold (spread) + P4 leftover V^T tiles 24..39 as second tiles on GEMM-only workgroups 192..207
# baseline (speedup 1.0000x reference)
.LBB0_1496:
	s_mul_hi_u32 s2, s41, 0xe8
	s_mul_i32 s2, s2, s39
	s_sub_i32 s2, 0xe8, s2
	s_sub_i32 s3, s2, s39
	s_cmp_ge_u32 s2, s39
	s_cselect_b32 s2, s3, s2
	s_sub_i32 s3, s2, s39
	s_cmp_ge_u32 s2, s39
	s_cselect_b32 s2, s3, s2
	s_sub_i32 s2, s40, s2
	s_ashr_i32 s3, s2, 31
	s_abs_i32 s2, s2
	s_mul_hi_u32 s4, s2, s41
	s_mul_i32 s4, s4, s39
	s_sub_i32 s2, s2, s4
	s_sub_i32 s4, s2, s39
	s_cmp_ge_u32 s2, s39
	s_cselect_b32 s2, s4, s2
	s_sub_i32 s4, s2, s39
	s_cmp_ge_u32 s2, s39
	s_cselect_b32 s2, s4, s2
	s_xor_b32 s2, s2, s3
	s_sub_i32 s28, s2, s3
	s_cmp_lt_u32 s89, 16
	s_cselect_b32 s28, 0x3e8, s28
	s_sub_u32 s2, s89, 0xc0
	s_cmp_lt_u32 s2, 16
	s_cbranch_scc0 .Lkvm_n
	s_add_u32 s28, s2, 24
